# v19 with non-temporal (nt) policy on the last-use streaming loads (residual stream and out-projection result) of the final stream-update phase
# speedup vs baseline: 1.0081x; 1.0043x over previous
.LBB0_1158:
	s_xor_b64 s[14:15], s[90:91], -1
	s_mov_b64 s[4:5], -1
	s_and_b64 vcc, exec, s[14:15]
	s_cbranch_vccz .LBB0_1175
	v_mov_b32_e32 v0, v157
	v_readlane_b32 s4, v255, 0
	v_ashrrev_i32_e32 v1, 6, v0
	s_nop 0
	v_add_u32_e32 v52, s4, v1
	v_cmp_gt_i32_e32 vcc, s33, v52
	s_and_saveexec_b64 s[4:5], vcc
	s_cbranch_execz .LBB0_1174
	s_waitcnt vmcnt(3)
	v_and_b32_e32 v32, 63, v0
	v_readlane_b32 s6, v255, 35
	v_ashrrev_i32_e32 v53, 31, v52
	v_lshlrev_b32_e32 v12, 5, v32
	v_readlane_b32 s7, v255, 36
	v_lshlrev_b64 v[24:25], 11, v[52:53]
	s_nop 3
	global_load_dwordx4 v[0:3], v12, s[6:7] offset:16
	global_load_dwordx4 v[4:7], v12, s[6:7]
	global_load_dwordx4 v[8:11], v12, s[6:7] offset:2064
	s_nop 0
	global_load_dwordx4 v[12:15], v12, s[6:7] offset:2048
	v_lshl_or_b32 v24, v32, 4, v24
	v_lshl_add_u64 v[20:21], s[56:57], 0, v[24:25]
	s_waitcnt vmcnt(6)
	v_lshl_add_u64 v[28:29], s[20:21], 0, v[24:25]
	global_load_dwordx4 v[16:19], v[20:21], off nt
	s_nop 0
	global_load_dwordx4 v[20:23], v[20:21], off offset:1024 nt
	s_nop 0
	global_load_dwordx4 v[24:27], v[28:29], off nt
	s_nop 0
	global_load_dwordx4 v[28:31], v[28:29], off offset:1024 nt
	v_cmp_gt_u32_e32 vcc, 16, v32
	v_mov_b32_e32 v55, 0
	v_lshlrev_b32_e32 v128, 2, v32
	s_and_saveexec_b64 s[6:7], vcc
	s_cbranch_execz .LBB0_1162
	v_lshlrev_b64 v[34:35], 6, v[52:53]
	v_lshl_add_u64 v[34:35], s[64:65], 0, v[34:35]
	v_lshl_add_u64 v[34:35], v[34:35], 0, v[128:129]
	global_load_dword v55, v[34:35], off

.LBB0_1166:
	v_add_u32_e32 v50, s18, v52
	v_cmp_gt_i32_e64 s[8:9], s33, v50
	v_ashrrev_i32_e32 v51, 31, v50
	s_and_saveexec_b64 s[6:7], s[8:9]
	s_cbranch_execz .LBB0_1170
	v_lshlrev_b64 v[40:41], 11, v[50:51]
	v_lshl_or_b32 v40, v54, 1, v40
	v_lshl_add_u64 v[32:33], s[56:57], 0, v[40:41]
	v_lshl_add_u64 v[40:41], s[20:21], 0, v[40:41]
	global_load_dwordx4 v[36:39], v[32:33], off nt
	s_nop 0
	global_load_dwordx4 v[32:35], v[32:33], off offset:1024 nt
	s_nop 0
	global_load_dwordx4 v[44:47], v[40:41], off nt
	s_nop 0
	global_load_dwordx4 v[40:43], v[40:41], off offset:1024 nt
	v_mov_b32_e32 v62, 0
	s_and_saveexec_b64 s[10:11], vcc
	s_cbranch_execz .LBB0_1169
	v_lshlrev_b64 v[62:63], 6, v[50:51]
	v_lshl_add_u64 v[62:63], v[48:49], 0, v[62:63]
	global_load_dword v62, v[62:63], off
	s_or_b64 exec, exec, s[10:11]
	s_or_b64 exec, exec, s[6:7]
	s_waitcnt vmcnt(5)
	s_branch .Le0_p7

.Le0_p7:
	ds_bpermute_b32 v53, v56, v55
	v_lshlrev_b32_e32 v66, 16, v24
	v_and_b32_e32 v67, 0xffff0000, v24
	v_lshlrev_b32_e32 v64, 16, v16
	v_and_b32_e32 v65, 0xffff0000, v16
	s_waitcnt lgkmcnt(0)
	v_add_f32_e32 v53, v55, v53
	ds_bpermute_b32 v63, v57, v53
	v_lshlrev_b32_e32 v68, 16, v25
	v_and_b32_e32 v69, 0xffff0000, v25
	v_lshlrev_b32_e32 v70, 16, v26
	v_and_b32_e32 v71, 0xffff0000, v26
	s_waitcnt lgkmcnt(0)
	v_add_f32_e32 v53, v53, v63
	ds_bpermute_b32 v63, v58, v53
	v_lshlrev_b32_e32 v72, 16, v27
	v_and_b32_e32 v73, 0xffff0000, v27
	v_lshlrev_b32_e32 v74, 16, v28
	v_and_b32_e32 v75, 0xffff0000, v28
	s_waitcnt lgkmcnt(0)
	v_add_f32_e32 v53, v53, v63
	ds_bpermute_b32 v63, v59, v53
	v_lshlrev_b32_e32 v76, 16, v29
	v_and_b32_e32 v77, 0xffff0000, v29
	v_lshlrev_b32_e32 v80, 16, v30
	v_and_b32_e32 v81, 0xffff0000, v30
	s_waitcnt lgkmcnt(0)
	v_add_f32_e32 v53, v53, v63
	ds_bpermute_b32 v63, v60, v53
	v_lshlrev_b32_e32 v82, 16, v31
	v_and_b32_e32 v83, 0xffff0000, v31
	s_waitcnt lgkmcnt(0)
	v_add_f32_e32 v53, v53, v63
	ds_bpermute_b32 v63, v61, v53
	s_waitcnt lgkmcnt(0)
	v_add_f32_e32 v53, v53, v63
	v_fmamk_f32 v53, v53, 0x3a800000, v155
	v_cmp_gt_f32_e64 s[10:11], s69, v53
	v_mul_f32_e32 v63, 0x4b800000, v53
	s_nop 0
	v_cndmask_b32_e64 v53, v53, v63, s[10:11]
	v_rsq_f32_e32 v53, v53
	s_nop 0
	v_mul_f32_e32 v63, 0x45800000, v53
	v_cndmask_b32_e64 v78, v53, v63, s[10:11]
	v_pk_mul_f32 v[66:67], v[78:79], v[66:67] op_sel_hi:[0,1]
	v_pk_fma_f32 v[64:65], v[4:5], v[66:67], v[64:65]
	v_lshlrev_b32_e32 v66, 16, v17
	v_and_b32_e32 v67, 0xffff0000, v17
	v_pk_mul_f32 v[68:69], v[78:79], v[68:69] op_sel_hi:[0,1]
	v_pk_fma_f32 v[66:67], v[6:7], v[68:69], v[66:67]
	v_lshlrev_b32_e32 v68, 16, v18
	v_and_b32_e32 v69, 0xffff0000, v18
	v_pk_mul_f32 v[70:71], v[78:79], v[70:71] op_sel_hi:[0,1]
	v_pk_fma_f32 v[68:69], v[0:1], v[70:71], v[68:69]
	v_lshlrev_b32_e32 v70, 16, v19
	v_and_b32_e32 v71, 0xffff0000, v19
	v_pk_mul_f32 v[72:73], v[78:79], v[72:73] op_sel_hi:[0,1]
	v_pk_fma_f32 v[70:71], v[2:3], v[72:73], v[70:71]
	v_lshlrev_b32_e32 v72, 16, v20
	v_and_b32_e32 v73, 0xffff0000, v20
	v_pk_mul_f32 v[74:75], v[78:79], v[74:75] op_sel_hi:[0,1]
	v_pk_fma_f32 v[72:73], v[12:13], v[74:75], v[72:73]
	v_lshlrev_b32_e32 v74, 16, v21
	v_and_b32_e32 v75, 0xffff0000, v21
	v_pk_mul_f32 v[76:77], v[78:79], v[76:77] op_sel_hi:[0,1]
	v_pk_fma_f32 v[74:75], v[14:15], v[76:77], v[74:75]
	v_lshlrev_b32_e32 v76, 16, v22
	v_and_b32_e32 v77, 0xffff0000, v22
	v_pk_mul_f32 v[80:81], v[78:79], v[80:81] op_sel_hi:[0,1]
	v_pk_fma_f32 v[76:77], v[8:9], v[80:81], v[76:77]
	v_lshlrev_b32_e32 v80, 16, v23
	v_and_b32_e32 v81, 0xffff0000, v23
	v_pk_mul_f32 v[78:79], v[78:79], v[82:83] op_sel_hi:[0,1]
	v_ashrrev_i32_e32 v53, 31, v52
	v_pk_fma_f32 v[78:79], v[10:11], v[78:79], v[80:81]
	v_lshlrev_b64 v[80:81], 12, v[52:53]
	v_lshl_or_b32 v80, v54, 2, v80
	v_lshl_add_u64 v[80:81], s[86:87], 0, v[80:81]
	global_store_dwordx4 v[80:81], v[64:67], off
	global_store_dwordx4 v[80:81], v[68:71], off offset:16
	global_store_dwordx4 v[80:81], v[72:75], off offset:2048
	global_store_dwordx4 v[80:81], v[76:79], off offset:2064
	s_and_saveexec_b64 s[10:11], s[8:9]
	s_cbranch_execz .LBB0_1165
	v_add_u32_e32 v52, s19, v52
	v_cmp_gt_i32_e64 s[8:9], s33, v52
	s_and_saveexec_b64 s[6:7], s[8:9]
	s_cbranch_execz .LBB0_1164
	v_ashrrev_i32_e32 v53, 31, v52
	v_lshlrev_b64 v[24:25], 11, v[52:53]
	v_lshl_or_b32 v24, v54, 1, v24
	v_lshl_add_u64 v[20:21], s[56:57], 0, v[24:25]
	v_lshl_add_u64 v[28:29], s[20:21], 0, v[24:25]
	global_load_dwordx4 v[16:19], v[20:21], off nt
	s_nop 0
	global_load_dwordx4 v[20:23], v[20:21], off offset:1024 nt
	s_nop 0
	global_load_dwordx4 v[24:27], v[28:29], off nt
	s_nop 0
	global_load_dwordx4 v[28:31], v[28:29], off offset:1024 nt
	v_mov_b32_e32 v55, 0
	s_and_saveexec_b64 s[8:9], vcc
	s_cbranch_execz .LBB0_1163
	v_lshlrev_b64 v[52:53], 6, v[52:53]
	v_lshl_add_u64 v[52:53], v[48:49], 0, v[52:53]
	global_load_dword v55, v[52:53], off
	s_or_b64 exec, exec, s[8:9]
	s_or_b64 exec, exec, s[6:7]
	s_waitcnt vmcnt(5)
	s_branch .Le0_p8
